# Weight transposes (P0 and P1's idle workgroups): the second gain vector of each 64x64 tile is requested with the tile's data instead of after the first half was consumed
# baseline (speedup 1.0000x reference)
; DI void transpose_tile(bf16_t* dst, int dst_ld, int n0, int nvalid, int nwrite, const float* src, int src_ld, int col0, int k0,
;                        const float* gain, float* ldsf, int tid) {
;     ...
;         for (int r = 0; r < 2; ++r) {
;             const int c = tid + NT * r, kk = c >> 4, n4 = (c & 15) * 4;
;             f32x4 v = __builtin_nontemporal_load((const f32x4*)(src + (size_t)(k0 + kk) * src_ld + col0 + n4));
;             const float g = gain ? gain[k0 + kk] : 1.0f;
;             float* d = ldsf + kk * 65 + n4;
;             d[0] = v[0] * g; d[1] = v[1] * g; d[2] = v[2] * g; d[3] = v[3] * g;
;         }
.LBB0_82:
	v_add_u32_e32 v22, s24, v21
	v_ashrrev_i32_e32 v23, 31, v22
	v_lshlrev_b64 v[6:7], 13, v[22:23]
	v_lshl_add_u64 v[4:5], v[4:5], 0, v[6:7]
	global_load_dwordx4 v[4:7], v[4:5], off nt
	s_and_b64 vcc, exec, s[6:7]
	s_cbranch_vccnz .Lwg_0_nog
	v_mov_b32_e32 v40, v22
	v_ashrrev_i32_e32 v41, 31, v22
	v_lshl_add_u64 v[40:41], v[40:41], 2, s[10:11]
	global_load_dword v18, v[40:41], off
	s_waitcnt vmcnt(2)
	s_branch .Lwg_0_go
.Lwg_0_nog:
	s_waitcnt vmcnt(1)
.Lwg_0_go:
	v_pk_mul_f32 v[0:1], v[0:1], v[20:21] op_sel_hi:[1,0]
	ds_write2_b32 v26, v0, v1 offset1:1
	v_pk_mul_f32 v[0:1], v[2:3], v[20:21] op_sel_hi:[1,0]
	s_and_b64 vcc, exec, s[6:7]
	ds_write2_b32 v27, v0, v1 offset1:1

; DI void transpose_tile(bf16_t* dst, int dst_ld, int n0, int nvalid, int nwrite, const float* src, int src_ld, int col0, int k0,
;                        const float* gain, float* ldsf, int tid) {
;     ...
;         for (int r = 0; r < 2; ++r) {
;             const int c = tid + NT * r, kk = c >> 4, n4 = (c & 15) * 4;
;             f32x4 v = __builtin_nontemporal_load((const f32x4*)(src + (size_t)(k0 + kk) * src_ld + col0 + n4));
;             const float g = gain ? gain[k0 + kk] : 1.0f;
;             float* d = ldsf + kk * 65 + n4;
;             d[0] = v[0] * g; d[1] = v[1] * g; d[2] = v[2] * g; d[3] = v[3] * g;
;         }
.LBB0_90:
	v_add_u32_e32 v22, s44, v21
	v_mad_i64_i32 v[4:5], s[46:47], v22, s53, v[4:5]
	global_load_dwordx4 v[4:7], v[4:5], off nt
	s_and_b64 vcc, exec, s[6:7]
	s_cbranch_vccnz .Lwg_1_nog
	v_mov_b32_e32 v40, v22
	v_ashrrev_i32_e32 v41, 31, v22
	v_lshl_add_u64 v[40:41], v[40:41], 2, s[8:9]
	global_load_dword v18, v[40:41], off
	s_waitcnt vmcnt(2)
	s_branch .Lwg_1_go

; DI void transpose_tile(bf16_t* dst, int dst_ld, int n0, int nvalid, int nwrite, const float* src, int src_ld, int col0, int k0,
;                        const float* gain, float* ldsf, int tid) {
;     ...
;         for (int r = 0; r < 2; ++r) {
;             const int c = tid + NT * r, kk = c >> 4, n4 = (c & 15) * 4;
;             f32x4 v = __builtin_nontemporal_load((const f32x4*)(src + (size_t)(k0 + kk) * src_ld + col0 + n4));
;             const float g = gain ? gain[k0 + kk] : 1.0f;
;             float* d = ldsf + kk * 65 + n4;
;             d[0] = v[0] * g; d[1] = v[1] * g; d[2] = v[2] * g; d[3] = v[3] * g;
;         }
.LBB0_99:
	v_add_u32_e32 v22, s44, v21
	v_mad_i64_i32 v[4:5], s[46:47], v22, s54, v[4:5]
	global_load_dwordx4 v[4:7], v[4:5], off nt
	s_and_b64 vcc, exec, s[6:7]
	s_cbranch_vccnz .Lwg_2_nog
	v_mov_b32_e32 v40, v22
	v_ashrrev_i32_e32 v41, 31, v22
	v_lshl_add_u64 v[40:41], v[40:41], 2, s[20:21]
	global_load_dword v18, v[40:41], off
	s_waitcnt vmcnt(2)
	s_branch .Lwg_2_go

; DI void transpose_tile(bf16_t* dst, int dst_ld, int n0, int nvalid, int nwrite, const float* src, int src_ld, int col0, int k0,
;                        const float* gain, float* ldsf, int tid) {
;     ...
;         for (int r = 0; r < 2; ++r) {
;             const int c = tid + NT * r, kk = c >> 4, n4 = (c & 15) * 4;
;             f32x4 v = __builtin_nontemporal_load((const f32x4*)(src + (size_t)(k0 + kk) * src_ld + col0 + n4));
;             const float g = gain ? gain[k0 + kk] : 1.0f;
;             float* d = ldsf + kk * 65 + n4;
;             d[0] = v[0] * g; d[1] = v[1] * g; d[2] = v[2] * g; d[3] = v[3] * g;
;         }
.LBB0_146:
	v_add_u32_e32 v22, s46, v21
	v_mad_i64_i32 v[4:5], s[44:45], v22, s54, v[4:5]
	global_load_dwordx4 v[4:7], v[4:5], off nt
	s_and_b64 vcc, exec, s[6:7]
	s_cbranch_vccnz .Lwg_4_nog
	v_mov_b32_e32 v40, v22
	v_ashrrev_i32_e32 v41, 31, v22
	v_lshl_add_u64 v[40:41], v[40:41], 2, s[20:21]
	global_load_dword v18, v[40:41], off
	s_waitcnt vmcnt(2)
	s_branch .Lwg_4_go

; DI void transpose_tile(bf16_t* dst, int dst_ld, int n0, int nvalid, int nwrite, const float* src, int src_ld, int col0, int k0,
;                        const float* gain, float* ldsf, int tid) {
;     ...
;         for (int r = 0; r < 2; ++r) {
;             const int c = tid + NT * r, kk = c >> 4, n4 = (c & 15) * 4;
;             f32x4 v = __builtin_nontemporal_load((const f32x4*)(src + (size_t)(k0 + kk) * src_ld + col0 + n4));
;             const float g = gain ? gain[k0 + kk] : 1.0f;
;             float* d = ldsf + kk * 65 + n4;
;             d[0] = v[0] * g; d[1] = v[1] * g; d[2] = v[2] * g; d[3] = v[3] * g;
;         }
.LBB0_407:
	v_add_u32_e32 v22, s8, v21
	v_ashrrev_i32_e32 v23, 31, v22
	v_lshlrev_b64 v[6:7], 13, v[22:23]
	v_lshl_add_u64 v[4:5], v[4:5], 0, v[6:7]
	global_load_dwordx4 v[4:7], v[4:5], off nt
	v_add_u32_e32 v28, v9, v19
	s_and_b64 vcc, exec, s[6:7]
	s_cbranch_vccnz .Lwg_5_nog
	v_mov_b32_e32 v40, v22
	v_ashrrev_i32_e32 v41, 31, v22
	v_lshl_add_u64 v[40:41], v[40:41], 2, s[22:23]
	global_load_dword v18, v[40:41], off
	s_waitcnt vmcnt(2)
	s_branch .Lwg_5_go

; DI void transpose_tile(bf16_t* dst, int dst_ld, int n0, int nvalid, int nwrite, const float* src, int src_ld, int col0, int k0,
;                        const float* gain, float* ldsf, int tid) {
;     ...
;             const int c = tid + NT * r, kk = c >> 4, n4 = (c & 15) * 4;
;             f32x4 v = __builtin_nontemporal_load((const f32x4*)(src + (size_t)(k0 + kk) * src_ld + col0 + n4));
;             const float g = gain ? gain[k0 + kk] : 1.0f;
;             float* d = ldsf + kk * 65 + n4;
;             d[0] = v[0] * g; d[1] = v[1] * g; d[2] = v[2] * g; d[3] = v[3] * g;
;         }
.Lwg_5_go:
	v_pk_mul_f32 v[0:1], v[0:1], v[20:21] op_sel_hi:[1,0]
	v_add_u32_e32 v29, 0x800, v28
	ds_write2_b32 v29, v0, v1 offset1:1
	v_pk_mul_f32 v[0:1], v[2:3], v[20:21] op_sel_hi:[1,0]
	v_add_u32_e32 v2, 0x808, v28
	s_and_b64 vcc, exec, s[6:7]
	ds_write2_b32 v2, v0, v1 offset1:1

; DI void transpose_tile(bf16_t* dst, int dst_ld, int n0, int nvalid, int nwrite, const float* src, int src_ld, int col0, int k0,
;                        const float* gain, float* ldsf, int tid) {
;     ...
;         for (int r = 0; r < 2; ++r) {
;             const int c = tid + NT * r, kk = c >> 4, n4 = (c & 15) * 4;
;             f32x4 v = __builtin_nontemporal_load((const f32x4*)(src + (size_t)(k0 + kk) * src_ld + col0 + n4));
;             const float g = gain ? gain[k0 + kk] : 1.0f;
;             float* d = ldsf + kk * 65 + n4;
;             d[0] = v[0] * g; d[1] = v[1] * g; d[2] = v[2] * g; d[3] = v[3] * g;
;         }
.LBB0_415:
	v_add_u32_e32 v22, s8, v21
	s_movk_i32 s9, 0x1800
	v_mad_i64_i32 v[4:5], s[10:11], v22, s9, v[4:5]
	global_load_dwordx4 v[4:7], v[4:5], off nt
	v_add_u32_e32 v23, v9, v19
	s_and_b64 vcc, exec, s[6:7]
	s_cbranch_vccnz .Lwg_6_nog
	v_mov_b32_e32 v40, v22
	v_ashrrev_i32_e32 v41, 31, v22
	v_lshl_add_u64 v[40:41], v[40:41], 2, s[20:21]
	global_load_dword v18, v[40:41], off
	s_waitcnt vmcnt(2)
	s_branch .Lwg_6_go

; DI void transpose_tile(bf16_t* dst, int dst_ld, int n0, int nvalid, int nwrite, const float* src, int src_ld, int col0, int k0,
;                        const float* gain, float* ldsf, int tid) {
;     ...
;             const int c = tid + NT * r, kk = c >> 4, n4 = (c & 15) * 4;
;             f32x4 v = __builtin_nontemporal_load((const f32x4*)(src + (size_t)(k0 + kk) * src_ld + col0 + n4));
;             const float g = gain ? gain[k0 + kk] : 1.0f;
;             float* d = ldsf + kk * 65 + n4;
;             d[0] = v[0] * g; d[1] = v[1] * g; d[2] = v[2] * g; d[3] = v[3] * g;
;         }
.Lwg_6_go:
	v_pk_mul_f32 v[0:1], v[0:1], v[20:21] op_sel_hi:[1,0]
	v_add_u32_e32 v28, 0x800, v23
	ds_write2_b32 v28, v0, v1 offset1:1
	v_pk_mul_f32 v[0:1], v[2:3], v[20:21] op_sel_hi:[1,0]
	v_add_u32_e32 v2, 0x808, v23
	s_and_b64 vcc, exec, s[6:7]
	ds_write2_b32 v2, v0, v1 offset1:1

; DI void transpose_tile(bf16_t* dst, int dst_ld, int n0, int nvalid, int nwrite, const float* src, int src_ld, int col0, int k0,
;                        const float* gain, float* ldsf, int tid) {
;     ...
;         for (int r = 0; r < 2; ++r) {
;             const int c = tid + NT * r, kk = c >> 4, n4 = (c & 15) * 4;
;             f32x4 v = __builtin_nontemporal_load((const f32x4*)(src + (size_t)(k0 + kk) * src_ld + col0 + n4));
;             const float g = gain ? gain[k0 + kk] : 1.0f;
;             float* d = ldsf + kk * 65 + n4;
;             d[0] = v[0] * g; d[1] = v[1] * g; d[2] = v[2] * g; d[3] = v[3] * g;
;         }
.LBB0_424:
	v_add_u32_e32 v22, s8, v21
	v_mad_i64_i32 v[4:5], s[10:11], v22, s66, v[4:5]
	global_load_dwordx4 v[4:7], v[4:5], off nt
	v_add_u32_e32 v23, v9, v19
	s_and_b64 vcc, exec, s[6:7]
	s_cbranch_vccnz .Lwg_7_nog
	v_mov_b32_e32 v40, v22
	v_ashrrev_i32_e32 v41, 31, v22
	v_lshl_add_u64 v[40:41], v[40:41], 2, s[36:37]
	global_load_dword v18, v[40:41], off
	s_waitcnt vmcnt(2)
	s_branch .Lwg_7_go

; DI void transpose_tile(bf16_t* dst, int dst_ld, int n0, int nvalid, int nwrite, const float* src, int src_ld, int col0, int k0,
;                        const float* gain, float* ldsf, int tid) {
;     ...
;         for (int r = 0; r < 2; ++r) {
;             const int c = tid + NT * r, kk = c >> 4, n4 = (c & 15) * 4;
;             f32x4 v = __builtin_nontemporal_load((const f32x4*)(src + (size_t)(k0 + kk) * src_ld + col0 + n4));
;             const float g = gain ? gain[k0 + kk] : 1.0f;
;             float* d = ldsf + kk * 65 + n4;
;             d[0] = v[0] * g; d[1] = v[1] * g; d[2] = v[2] * g; d[3] = v[3] * g;
;         }
.LBB0_471:
	v_add_u32_e32 v22, s82, v21
	v_mad_i64_i32 v[4:5], s[8:9], v22, s66, v[4:5]
	global_load_dwordx4 v[4:7], v[4:5], off nt
	v_add_u32_e32 v23, v9, v19
	s_and_b64 vcc, exec, s[6:7]
	s_cbranch_vccnz .Lwg_9_nog
	v_mov_b32_e32 v40, v22
	v_ashrrev_i32_e32 v41, 31, v22
	v_lshl_add_u64 v[40:41], v[40:41], 2, s[36:37]
	global_load_dword v18, v[40:41], off
	s_waitcnt vmcnt(2)
	s_branch .Lwg_9_go
